# attention: epilogue gate loads issued in the last K-tile iteration after the QK MFMAs (hidden under softmax and PV)
# speedup vs baseline: 1.0250x; 1.0012x over previous
.LBB0_693:
	s_add_i32 s17, s14, s16
	s_bitcmp1_b32 s16, 0
	s_cselect_b32 s8, 0x8800, 0
	s_add_i32 s23, s8, 0
	v_add_u32_e32 v0, s23, v172
	ds_read_b128 v[0:3], v0
	v_add_u32_e32 v209, s23, v174
	ds_read_b128 v[234:237], v209
	v_add_u32_e32 v209, s23, v175
	s_and_b32 s8, s17, -5
	s_cmp_eq_u32 s8, 0
	s_waitcnt lgkmcnt(1)
	v_mfma_f32_32x32x16_bf16 v[16:31], v[0:3], v[122:125], 0
	v_add_u32_e32 v0, s23, v173
	ds_read_b128 v[0:3], v0
	s_waitcnt lgkmcnt(1)
	v_mfma_f32_32x32x16_bf16 v[16:31], v[234:237], v[126:129], v[16:31]
	ds_read_b128 v[234:237], v209
	v_add_u32_e32 v209, s23, v176
	s_waitcnt lgkmcnt(1)
	v_mfma_f32_32x32x16_bf16 v[0:15], v[0:3], v[122:125], 0
	s_waitcnt lgkmcnt(0)
	v_mfma_f32_32x32x16_bf16 v[0:15], v[234:237], v[126:129], v[0:15]
	ds_read_b128 v[234:237], v209
	v_add_u32_e32 v209, s23, v177
	s_waitcnt lgkmcnt(0)
	v_mfma_f32_32x32x16_bf16 v[16:31], v[234:237], v[98:101], v[16:31]
	ds_read_b128 v[234:237], v209
	v_add_u32_e32 v209, s23, v185
	s_waitcnt lgkmcnt(0)
	v_mfma_f32_32x32x16_bf16 v[0:15], v[234:237], v[98:101], v[0:15]
	ds_read_b128 v[234:237], v209
	v_add_u32_e32 v209, s23, v190
	s_waitcnt lgkmcnt(0)
	v_mfma_f32_32x32x16_bf16 v[16:31], v[234:237], v[102:105], v[16:31]
	ds_read_b128 v[234:237], v209
	v_add_u32_e32 v209, s23, v191
	s_waitcnt lgkmcnt(0)
	v_mfma_f32_32x32x16_bf16 v[0:15], v[234:237], v[102:105], v[0:15]
	ds_read_b128 v[234:237], v209
	v_add_u32_e32 v209, s23, v192
	s_waitcnt lgkmcnt(0)
	v_mfma_f32_32x32x16_bf16 v[16:31], v[234:237], v[106:109], v[16:31]
	ds_read_b128 v[234:237], v209
	v_add_u32_e32 v209, s23, v193
	s_waitcnt lgkmcnt(0)
	v_mfma_f32_32x32x16_bf16 v[0:15], v[234:237], v[106:109], v[0:15]
	ds_read_b128 v[234:237], v209
	v_add_u32_e32 v209, s23, v194
	s_waitcnt lgkmcnt(0)
	v_mfma_f32_32x32x16_bf16 v[16:31], v[234:237], v[110:113], v[16:31]
	ds_read_b128 v[234:237], v209
	v_add_u32_e32 v209, s23, v195
	s_waitcnt lgkmcnt(0)
	v_mfma_f32_32x32x16_bf16 v[0:15], v[234:237], v[110:113], v[0:15]
	ds_read_b128 v[234:237], v209
	v_add_u32_e32 v209, s23, v196
	s_waitcnt lgkmcnt(0)
	v_mfma_f32_32x32x16_bf16 v[16:31], v[234:237], v[114:117], v[16:31]
	ds_read_b128 v[234:237], v209
	v_add_u32_e32 v209, s23, v197
	s_waitcnt lgkmcnt(0)
	v_mfma_f32_32x32x16_bf16 v[0:15], v[234:237], v[114:117], v[0:15]
	ds_read_b128 v[234:237], v209
	v_add_u32_e32 v209, s23, v198
	s_waitcnt lgkmcnt(0)
	v_mfma_f32_32x32x16_bf16 v[16:31], v[234:237], v[118:121], v[16:31]
	ds_read_b128 v[234:237], v209
	s_waitcnt lgkmcnt(0)
	v_mfma_f32_32x32x16_bf16 v[0:15], v[234:237], v[118:121], v[0:15]
	s_cselect_b32 s9, 1, 0
	s_cmp_lt_i32 s17, s15
	s_cbranch_scc1 .Lattn_nogate
	v_lshrrev_b32_e32 v138, 4, v146
	v_lshrrev_b32_e32 v140, 1, v168
	v_add_u32_e32 v138, v138, v140
	v_and_b32_e32 v140, 15, v146
	v_add_u32_e32 v138, v159, v138
	v_mul_lo_u32 v138, v138, s97
	v_lshlrev_b32_e32 v140, 4, v140
	v_lshl_add_u32 v140, v160, 1, v140
	v_add_u32_e32 v130, v138, v140
	v_add_u32_e32 v130, 0x1400, v130
	v_add_u32_e32 v131, 0xb000, v130
	v_add_u32_e32 v132, 0xb000, v131
	v_add_u32_e32 v133, 0xb000, v132
	v_add_u32_e32 v134, 0xb000, v133
	v_add_u32_e32 v135, 0xb000, v134
	v_add_u32_e32 v136, 0xb000, v135
	v_add_u32_e32 v137, 0xb000, v136
	global_load_dwordx4 v[98:101], v130, s[0:1]
	global_load_dwordx4 v[102:105], v131, s[0:1]
	global_load_dwordx4 v[106:109], v132, s[0:1]
	global_load_dwordx4 v[110:113], v133, s[0:1]
	global_load_dwordx4 v[114:117], v134, s[0:1]
	global_load_dwordx4 v[118:121], v135, s[0:1]
	global_load_dwordx4 v[122:125], v136, s[0:1]
	global_load_dwordx4 v[126:129], v137, s[0:1]
.Lattn_nogate:
	s_cmp_lg_u32 s9, 0
	s_nop 8
	v_sub_f32_e32 v16, v16, v206
	v_sub_f32_e32 v17, v17, v206
	v_sub_f32_e32 v18, v18, v206
	v_sub_f32_e32 v19, v19, v206
	v_sub_f32_e32 v20, v20, v206
	v_sub_f32_e32 v21, v21, v206
	v_sub_f32_e32 v22, v22, v206
	v_sub_f32_e32 v23, v23, v206
	v_sub_f32_e32 v24, v24, v206
	v_sub_f32_e32 v25, v25, v206
	v_sub_f32_e32 v26, v26, v206
	v_sub_f32_e32 v27, v27, v206
	v_sub_f32_e32 v28, v28, v206
	v_sub_f32_e32 v29, v29, v206
	v_sub_f32_e32 v30, v30, v206
	v_sub_f32_e32 v31, v31, v206
	v_sub_f32_e32 v209, v0, v206
	v_sub_f32_e32 v234, v1, v206
	v_sub_f32_e32 v235, v2, v206
	v_sub_f32_e32 v236, v3, v206
	v_sub_f32_e32 v237, v4, v206
	v_sub_f32_e32 v238, v5, v206
	v_sub_f32_e32 v239, v6, v206
	v_sub_f32_e32 v240, v7, v206
	v_sub_f32_e32 v241, v8, v206
	v_sub_f32_e32 v242, v9, v206
	v_sub_f32_e32 v243, v10, v206
	v_sub_f32_e32 v244, v11, v206
	v_sub_f32_e32 v245, v12, v206
	v_sub_f32_e32 v246, v13, v206
	v_sub_f32_e32 v247, v14, v206
	v_sub_f32_e32 v248, v15, v206
	v_exp_f32_e32 v0, v16
	v_exp_f32_e32 v1, v17
	v_exp_f32_e32 v2, v18
	v_exp_f32_e32 v3, v19
	v_exp_f32_e32 v4, v20
	v_exp_f32_e32 v5, v21
	v_exp_f32_e32 v6, v22
	v_exp_f32_e32 v7, v23
	v_exp_f32_e32 v8, v24
	v_exp_f32_e32 v9, v25
	v_exp_f32_e32 v10, v26
	v_exp_f32_e32 v11, v27
	v_exp_f32_e32 v12, v28
	v_exp_f32_e32 v13, v29
	v_exp_f32_e32 v14, v30
	v_exp_f32_e32 v15, v31
	v_exp_f32_e32 v16, v209
	v_exp_f32_e32 v17, v234
	v_exp_f32_e32 v18, v235
	v_exp_f32_e32 v19, v236
	v_exp_f32_e32 v20, v237
	v_exp_f32_e32 v21, v238
	v_exp_f32_e32 v22, v239
	v_exp_f32_e32 v23, v240
	v_exp_f32_e32 v24, v241
	v_exp_f32_e32 v25, v242
	v_exp_f32_e32 v26, v243
	v_exp_f32_e32 v27, v244
	v_exp_f32_e32 v28, v245
	v_exp_f32_e32 v29, v246
	v_exp_f32_e32 v30, v247
	v_exp_f32_e32 v31, v248
	s_cbranch_scc1 .LBB0_704
	v_add_f32_e32 v209, v208, v0
	v_add_f32_e32 v209, v1, v209
	v_add_f32_e32 v209, v2, v209
	v_add_f32_e32 v209, v3, v209
	v_add_f32_e32 v209, v4, v209
	v_add_f32_e32 v209, v5, v209
	v_add_f32_e32 v209, v6, v209
	v_add_f32_e32 v209, v7, v209
	v_add_f32_e32 v209, v8, v209
	v_add_f32_e32 v209, v9, v209
	v_add_f32_e32 v209, v10, v209
	v_add_f32_e32 v209, v11, v209
	v_add_f32_e32 v209, v12, v209
	v_add_f32_e32 v209, v13, v209
	v_add_f32_e32 v209, v14, v209
	v_add_f32_e32 v209, v15, v209
	v_add_f32_e32 v209, v16, v209
	v_add_f32_e32 v209, v17, v209
	v_add_f32_e32 v209, v18, v209
	v_add_f32_e32 v209, v19, v209
	v_add_f32_e32 v209, v20, v209
	v_add_f32_e32 v209, v21, v209
	v_add_f32_e32 v209, v22, v209
	v_add_f32_e32 v209, v23, v209
	v_add_f32_e32 v209, v24, v209
	v_add_f32_e32 v209, v25, v209
	v_add_f32_e32 v209, v26, v209
	v_add_f32_e32 v209, v27, v209
	v_add_f32_e32 v209, v28, v209
	v_add_f32_e32 v209, v29, v209
	v_add_f32_e32 v209, v30, v209
	v_add_f32_e32 v209, v31, v209
	s_cbranch_execnz .LBB0_696

.LBB0_705:
	ds_bpermute_b32 v0, v147, v209
	v_lshrrev_b32_e32 v11, 4, v146
	v_lshrrev_b32_e32 v12, 1, v168
	v_add_u32_e32 v11, v11, v12
	v_and_b32_e32 v13, 15, v146
	v_add_u32_e32 v14, v159, v11
	v_mul_lo_u32 v15, v14, s97
	v_lshlrev_b32_e32 v16, 4, v13
	v_lshl_add_u32 v16, v160, 1, v16
	v_lshl_add_u32 v26, v14, 12, v16
	v_add_u32_e32 v26, 0x55d0400, v26
	v_mul_u32_u24_e32 v8, 0x90, v146
	v_sub_u32_e32 v9, v204, v8
	v_lshlrev_b32_e32 v10, 1, v168
	v_sub_u32_e32 v9, v9, v10
	s_movk_i32 s14, 0x210
	v_mad_u32_u24 v24, v168, s14, v9
	v_lshl_add_u32 v24, v146, 2, v24
	v_mad_u32_u24 v25, v11, s14, v9
	v_lshl_add_u32 v25, v13, 5, v25
	s_and_saveexec_b64 s[8:9], s[4:5]
	s_cbranch_execz .LBB0_687
	v_sub_f32_e32 v1, v157, v206
	v_cmp_gt_f32_e32 vcc, s20, v1
	s_waitcnt lgkmcnt(0)
	v_add_f32_e32 v0, v209, v0
	v_cndmask_b32_e32 v2, 0, v228, vcc
	v_add_f32_e32 v1, v1, v2
	v_exp_f32_e32 v1, v1
	v_cndmask_b32_e32 v2, 0, v223, vcc
	v_ldexp_f32 v1, v1, v2
	v_add_f32_e32 v0, v1, v0
	v_div_scale_f32 v1, s[14:15], v0, v0, 1.0
	v_rcp_f32_e32 v2, v1
	v_div_scale_f32 v3, vcc, 1.0, v0, 1.0
	v_fma_f32 v4, -v1, v2, 1.0
	v_fmac_f32_e32 v2, v4, v2
	v_mul_f32_e32 v4, v3, v2
	v_fma_f32 v5, -v1, v4, v3
	v_fmac_f32_e32 v4, v5, v2
	v_fma_f32 v1, -v1, v4, v3
	v_div_fmas_f32 v1, v1, v2, v4
	v_div_fixup_f32 v0, v1, v0, 1.0
	ds_write_b32 v169, v0
	s_branch .LBB0_687
